# P5 K-loop: all s_setprio removed; with barrier edits + P2 plain stores
# baseline (speedup 1.0000x reference)
; #define PG8_STAGE(bufoff, gbase, voff) do { _Pragma("unroll") for (int _i = 0; _i < 2; ++_i) \
;         __builtin_amdgcn_global_load_lds((const unsigned*)((const char*)(gbase) + (voff)[_i]), (PG8_LAS unsigned*)(lds + (bufoff) + ldsw + _i * 8192), 16, 0, 0); } while (0)
; #define PG8_LDA(dst, b, h) do { _Pragma("unroll") for (int m = 0; m < 4; ++m) _Pragma("unroll") for (int k = 0; k < 2; ++k) dst[m][k] = *(const PG8_LAS bf16x8*)(lds + PG8_SA(b, h) + aoff + m * 2048 + k * 1024); } while (0)
; #define PG8_LDB(dst, b, h) do { _Pragma("unroll") for (int n = 0; n < 2; ++n) _Pragma("unroll") for (int k = 0; k < 2; ++k) dst[n][k] = *(const PG8_LAS bf16x8*)(lds + PG8_SB(b, h) + boff + n * 2048 + k * 1024); } while (0)
; #define PG8_MMA(ai, bj, At, Bt) do { __builtin_amdgcn_s_setprio(1); _Pragma("unroll") for (int m = 0; m < 4; ++m) _Pragma("unroll") for (int n = 0; n < 2; ++n) _Pragma("unroll") for (int k = 0; k < 2; ++k) \
;         acc[ai][bj][m][n] = __builtin_amdgcn_mfma_f32_16x16x32_bf16(Bt[n][k], At[m][k], acc[ai][bj][m][n], 0, 0, 0); __builtin_amdgcn_s_setprio(0); } while (0)
; #define PG8_WAIT_V(n) asm volatile("s_waitcnt vmcnt(" #n ")" ::: "memory")
; #define PG8_WAIT_L(n) asm volatile("s_waitcnt lgkmcnt(" #n ")" ::: "memory")
; #define PG8_BAR __builtin_amdgcn_s_barrier()
; #define PG8_SCHED __builtin_amdgcn_sched_barrier(0)
; template <class Epi, class Sched, bool ALIGN_EPI = false, bool SP2 = false>
; __device__ __forceinline__ void gemm_phase(PG8_LAS unsigned char* lds, const Gemm g, const Sched& S, const Epi& E, volatile PG8_LAS unsigned* sw = nullptr) {
;     ...
;             PG8_LDB(B0, 0, 0); PG8_LDB(B1, 0, 1); PG8_SCHED; PG8_LDA(At, 0, 0); PG8_STAGE(PG8_SA(1, 1), a1 + hstep, voffA);
;             PG8_WAIT_V(8); PG8_WAIT_L(0); PG8_BAR; PG8_MMA(0, 0, At, B0); PG8_MMA(0, 1, At, B1); PG8_BAR; PG8_SCHED;
;             PG8_LDA(At, 0, 1); PG8_STAGE(PG8_SB(0, 0), b2, voffB); PG8_STAGE(PG8_SB(0, 1), b2 + hstep, voffB); PG8_STAGE(PG8_SA(0, 0), a2, voffA);
.LBB0_532:
	ds_read_b128 v[130:133], v230
	ds_read_b128 v[134:137], v230 offset:1024
	ds_read_b128 v[138:141], v230 offset:2048
	ds_read_b128 v[142:145], v230 offset:3072
	ds_read_b128 v[146:149], v231
	ds_read_b128 v[150:153], v231 offset:1024
	ds_read_b128 v[168:171], v231 offset:2048
	ds_read_b128 v[172:175], v231 offset:3072
	s_add_u32 s2, s0, 0x10000
	s_addc_u32 s3, s1, 0
	s_cmp_eq_u32 s85, 12
	s_cselect_b32 s8, s57, s2
	s_cselect_b32 s9, s37, s3
	s_cselect_b32 s6, s66, s67
	s_cselect_b32 s7, s39, s84
	s_add_u32 s4, s8, 0x8000
	s_addc_u32 s5, s9, 0
	v_lshl_add_u64 v[208:209], s[0:1], 0, v[164:165]
	s_add_i32 m0, s15, 0xc000
	ds_read_b128 v[176:179], v232
	ds_read_b128 v[180:183], v232 offset:1024
	ds_read_b128 v[184:187], v232 offset:2048
	ds_read_b128 v[188:191], v232 offset:3072
	ds_read_b128 v[192:195], v232 offset:4096
	ds_read_b128 v[196:199], v232 offset:5120
	ds_read_b128 v[200:203], v232 offset:6144
	ds_read_b128 v[204:207], v232 offset:7168
	global_load_lds_dwordx4 v[208:209], off
	v_lshl_add_u64 v[208:209], s[0:1], 0, v[166:167]
	s_add_i32 m0, s15, 0xe000
	s_nop 0
	global_load_lds_dwordx4 v[208:209], off
	s_waitcnt vmcnt(8)
	s_waitcnt lgkmcnt(0)
	s_barrier
	s_waitcnt lgkmcnt(0)
	v_mfma_f32_16x16x32_bf16 v[118:121], v[130:133], v[176:179], v[118:121]
	v_mfma_f32_16x16x32_bf16 v[122:125], v[138:141], v[176:179], v[122:125]
	v_mfma_f32_16x16x32_bf16 v[78:81], v[130:133], v[184:187], v[78:81]
	v_mfma_f32_16x16x32_bf16 v[74:77], v[138:141], v[184:187], v[74:77]
	v_mfma_f32_16x16x32_bf16 v[58:61], v[130:133], v[192:195], v[58:61]
	v_mfma_f32_16x16x32_bf16 v[54:57], v[138:141], v[192:195], v[54:57]
	v_mfma_f32_16x16x32_bf16 v[126:129], v[130:133], v[200:203], v[126:129]
	v_mfma_f32_16x16x32_bf16 v[114:117], v[138:141], v[200:203], v[114:117]
	v_mfma_f32_16x16x32_bf16 v[118:121], v[134:137], v[180:183], v[118:121]
	v_mfma_f32_16x16x32_bf16 v[122:125], v[142:145], v[180:183], v[122:125]
	v_mfma_f32_16x16x32_bf16 v[78:81], v[134:137], v[188:191], v[78:81]
	v_mfma_f32_16x16x32_bf16 v[74:77], v[142:145], v[188:191], v[74:77]
	v_mfma_f32_16x16x32_bf16 v[58:61], v[134:137], v[196:199], v[58:61]
	v_mfma_f32_16x16x32_bf16 v[54:57], v[142:145], v[196:199], v[54:57]
	v_mfma_f32_16x16x32_bf16 v[126:129], v[134:137], v[204:207], v[126:129]
	v_mfma_f32_16x16x32_bf16 v[114:117], v[142:145], v[204:207], v[114:117]
	v_mfma_f32_16x16x32_bf16 v[110:113], v[146:149], v[176:179], v[110:113]
	v_mfma_f32_16x16x32_bf16 v[98:101], v[168:171], v[176:179], v[98:101]
	v_mfma_f32_16x16x32_bf16 v[70:73], v[146:149], v[184:187], v[70:73]
	v_mfma_f32_16x16x32_bf16 v[66:69], v[168:171], v[184:187], v[66:69]
	v_mfma_f32_16x16x32_bf16 v[42:45], v[146:149], v[192:195], v[42:45]
	v_mfma_f32_16x16x32_bf16 v[34:37], v[168:171], v[192:195], v[34:37]
	v_mfma_f32_16x16x32_bf16 v[102:105], v[146:149], v[200:203], v[102:105]
	v_mfma_f32_16x16x32_bf16 v[90:93], v[168:171], v[200:203], v[90:93]
	v_mfma_f32_16x16x32_bf16 v[110:113], v[150:153], v[180:183], v[110:113]
	v_mfma_f32_16x16x32_bf16 v[98:101], v[172:175], v[180:183], v[98:101]
	v_mfma_f32_16x16x32_bf16 v[70:73], v[150:153], v[188:191], v[70:73]
	v_mfma_f32_16x16x32_bf16 v[66:69], v[172:175], v[188:191], v[66:69]
	v_mfma_f32_16x16x32_bf16 v[42:45], v[150:153], v[196:199], v[42:45]
	v_mfma_f32_16x16x32_bf16 v[34:37], v[172:175], v[196:199], v[34:37]
	v_mfma_f32_16x16x32_bf16 v[102:105], v[150:153], v[204:207], v[102:105]
	v_mfma_f32_16x16x32_bf16 v[90:93], v[172:175], v[204:207], v[90:93]
	s_barrier
	s_add_i32 s0, s75, s13
	v_lshl_add_u64 v[208:209], s[6:7], 0, v[156:157]
	s_mov_b32 m0, s0
	ds_read_b128 v[176:179], v232 offset:16384
	ds_read_b128 v[180:183], v232 offset:17408
	ds_read_b128 v[184:187], v232 offset:18432
	ds_read_b128 v[188:191], v232 offset:19456
	ds_read_b128 v[192:195], v232 offset:20480
	ds_read_b128 v[196:199], v232 offset:21504
	ds_read_b128 v[200:203], v232 offset:22528
	ds_read_b128 v[204:207], v232 offset:23552
	global_load_lds_dwordx4 v[208:209], off
	s_add_i32 m0, s0, 0x2000
	s_add_u32 s0, s6, 0x4000
	v_lshl_add_u64 v[208:209], s[6:7], 0, v[160:161]
	s_addc_u32 s1, s7, 0
	s_add_i32 s86, s80, s13
	global_load_lds_dwordx4 v[208:209], off
	v_lshl_add_u64 v[208:209], s[0:1], 0, v[156:157]
	s_mov_b32 m0, s86
	s_nop 0
	global_load_lds_dwordx4 v[208:209], off
	v_lshl_add_u64 v[208:209], s[0:1], 0, v[160:161]
	s_add_i32 m0, s86, 0x2000
	s_nop 0
	global_load_lds_dwordx4 v[208:209], off
	v_lshl_add_u64 v[208:209], s[8:9], 0, v[154:155]
	s_mov_b32 m0, s15
	s_nop 0
	global_load_lds_dwordx4 v[208:209], off
	v_lshl_add_u64 v[208:209], s[8:9], 0, v[158:159]
	s_mov_b32 m0, s33
	s_nop 0
	global_load_lds_dwordx4 v[208:209], off
	s_waitcnt vmcnt(8)
	s_waitcnt lgkmcnt(0)
	s_barrier
; #define PG8_STAGE(bufoff, gbase, voff) do { _Pragma("unroll") for (int _i = 0; _i < 2; ++_i) \
;         __builtin_amdgcn_global_load_lds((const unsigned*)((const char*)(gbase) + (voff)[_i]), (PG8_LAS unsigned*)(lds + (bufoff) + ldsw + _i * 8192), 16, 0, 0); } while (0)
; #define PG8_LDA(dst, b, h) do { _Pragma("unroll") for (int m = 0; m < 4; ++m) _Pragma("unroll") for (int k = 0; k < 2; ++k) dst[m][k] = *(const PG8_LAS bf16x8*)(lds + PG8_SA(b, h) + aoff + m * 2048 + k * 1024); } while (0)
; #define PG8_LDB(dst, b, h) do { _Pragma("unroll") for (int n = 0; n < 2; ++n) _Pragma("unroll") for (int k = 0; k < 2; ++k) dst[n][k] = *(const PG8_LAS bf16x8*)(lds + PG8_SB(b, h) + boff + n * 2048 + k * 1024); } while (0)
; #define PG8_MMA(ai, bj, At, Bt) do { __builtin_amdgcn_s_setprio(1); _Pragma("unroll") for (int m = 0; m < 4; ++m) _Pragma("unroll") for (int n = 0; n < 2; ++n) _Pragma("unroll") for (int k = 0; k < 2; ++k) \
;         acc[ai][bj][m][n] = __builtin_amdgcn_mfma_f32_16x16x32_bf16(Bt[n][k], At[m][k], acc[ai][bj][m][n], 0, 0, 0); __builtin_amdgcn_s_setprio(0); } while (0)
; #define PG8_WAIT_V(n) asm volatile("s_waitcnt vmcnt(" #n ")" ::: "memory")
; #define PG8_WAIT_L(n) asm volatile("s_waitcnt lgkmcnt(" #n ")" ::: "memory")
; #define PG8_BAR __builtin_amdgcn_s_barrier()
; #define PG8_SCHED __builtin_amdgcn_sched_barrier(0)
; template <class Epi, class Sched, bool ALIGN_EPI = false, bool SP2 = false>
; __device__ __forceinline__ void gemm_phase(PG8_LAS unsigned char* lds, const Gemm g, const Sched& S, const Epi& E, volatile PG8_LAS unsigned* sw = nullptr) {
;     ...
;             PG8_WAIT_V(8); PG8_WAIT_L(0); PG8_BAR; PG8_MMA(1, 0, At, B0); PG8_MMA(1, 1, At, B1); PG8_BAR; PG8_SCHED;
;             PG8_LDB(B0, 1, 0); PG8_LDB(B1, 1, 1); PG8_SCHED; PG8_LDA(At, 1, 0); PG8_STAGE(PG8_SA(0, 1), a2 + hstep, voffA);
;             PG8_WAIT_V(8); PG8_WAIT_L(0); PG8_BAR; PG8_MMA(0, 0, At, B0); PG8_MMA(0, 1, At, B1); PG8_BAR; PG8_SCHED;
	s_waitcnt lgkmcnt(0)
	v_mfma_f32_16x16x32_bf16 v[94:97], v[130:133], v[176:179], v[94:97]
	v_mfma_f32_16x16x32_bf16 v[106:109], v[138:141], v[176:179], v[106:109]
	v_mfma_f32_16x16x32_bf16 v[38:41], v[130:133], v[184:187], v[38:41]
	v_mfma_f32_16x16x32_bf16 v[26:29], v[138:141], v[184:187], v[26:29]
	v_mfma_f32_16x16x32_bf16 v[46:49], v[130:133], v[192:195], v[46:49]
	v_mfma_f32_16x16x32_bf16 v[62:65], v[138:141], v[192:195], v[62:65]
	v_mfma_f32_16x16x32_bf16 v[2:5], v[130:133], v[200:203], v[2:5]
	v_mfma_f32_16x16x32_bf16 v[18:21], v[138:141], v[200:203], v[18:21]
	v_mfma_f32_16x16x32_bf16 v[94:97], v[134:137], v[180:183], v[94:97]
	v_mfma_f32_16x16x32_bf16 v[106:109], v[142:145], v[180:183], v[106:109]
	v_mfma_f32_16x16x32_bf16 v[38:41], v[134:137], v[188:191], v[38:41]
	v_mfma_f32_16x16x32_bf16 v[26:29], v[142:145], v[188:191], v[26:29]
	v_mfma_f32_16x16x32_bf16 v[46:49], v[134:137], v[196:199], v[46:49]
	v_mfma_f32_16x16x32_bf16 v[62:65], v[142:145], v[196:199], v[62:65]
	v_mfma_f32_16x16x32_bf16 v[2:5], v[134:137], v[204:207], v[2:5]
	v_mfma_f32_16x16x32_bf16 v[18:21], v[142:145], v[204:207], v[18:21]
	v_mfma_f32_16x16x32_bf16 v[86:89], v[146:149], v[176:179], v[86:89]
	v_mfma_f32_16x16x32_bf16 v[82:85], v[168:171], v[176:179], v[82:85]
	v_mfma_f32_16x16x32_bf16 v[14:17], v[146:149], v[184:187], v[14:17]
	v_mfma_f32_16x16x32_bf16 v[10:13], v[168:171], v[184:187], v[10:13]
	v_mfma_f32_16x16x32_bf16 v[30:33], v[146:149], v[192:195], v[30:33]
	v_mfma_f32_16x16x32_bf16 v[50:53], v[168:171], v[192:195], v[50:53]
	v_mfma_f32_16x16x32_bf16 v[6:9], v[146:149], v[200:203], v[6:9]
	v_mfma_f32_16x16x32_bf16 v[22:25], v[168:171], v[200:203], v[22:25]
	v_mfma_f32_16x16x32_bf16 v[86:89], v[150:153], v[180:183], v[86:89]
	v_mfma_f32_16x16x32_bf16 v[82:85], v[172:175], v[180:183], v[82:85]
	v_mfma_f32_16x16x32_bf16 v[14:17], v[150:153], v[188:191], v[14:17]
	v_mfma_f32_16x16x32_bf16 v[10:13], v[172:175], v[188:191], v[10:13]
	v_mfma_f32_16x16x32_bf16 v[30:33], v[150:153], v[196:199], v[30:33]
	v_mfma_f32_16x16x32_bf16 v[50:53], v[172:175], v[196:199], v[50:53]
	v_mfma_f32_16x16x32_bf16 v[6:9], v[150:153], v[204:207], v[6:9]
	v_mfma_f32_16x16x32_bf16 v[22:25], v[172:175], v[204:207], v[22:25]
	s_barrier
	s_add_i32 s86, 0, 0x18000
	s_add_i32 s87, 0, 0x1c000
	v_add_u32_e32 v142, s86, v229
	v_add_u32_e32 v162, s87, v229
	ds_read_b128 v[130:133], v142
	ds_read_b128 v[134:137], v142 offset:1024
	ds_read_b128 v[138:141], v142 offset:2048
	ds_read_b128 v[142:145], v142 offset:3072
	ds_read_b128 v[146:149], v162
	ds_read_b128 v[150:153], v162 offset:1024
	ds_read_b128 v[168:171], v162 offset:2048
	ds_read_b128 v[172:175], v162 offset:3072
	s_add_u32 s0, s8, 0x4000
	s_addc_u32 s1, s9, 0
	s_mov_b32 m0, s40
	v_lshl_add_u64 v[208:209], s[0:1], 0, v[154:155]
	ds_read_b128 v[176:179], v232 offset:32768
	ds_read_b128 v[180:183], v232 offset:33792
	ds_read_b128 v[184:187], v232 offset:34816
	ds_read_b128 v[188:191], v232 offset:35840
	ds_read_b128 v[192:195], v232 offset:36864
	ds_read_b128 v[196:199], v232 offset:37888
	ds_read_b128 v[200:203], v232 offset:38912
	ds_read_b128 v[204:207], v232 offset:39936
	global_load_lds_dwordx4 v[208:209], off
	v_lshl_add_u64 v[208:209], s[0:1], 0, v[158:159]
	s_mov_b32 m0, s41
	s_nop 0
	global_load_lds_dwordx4 v[208:209], off
	s_waitcnt vmcnt(8)
	s_waitcnt lgkmcnt(0)
	s_barrier
	s_waitcnt lgkmcnt(0)
	v_mfma_f32_16x16x32_bf16 v[118:121], v[130:133], v[176:179], v[118:121]
	v_mfma_f32_16x16x32_bf16 v[122:125], v[138:141], v[176:179], v[122:125]
	v_mfma_f32_16x16x32_bf16 v[78:81], v[130:133], v[184:187], v[78:81]
	v_mfma_f32_16x16x32_bf16 v[74:77], v[138:141], v[184:187], v[74:77]
	v_mfma_f32_16x16x32_bf16 v[58:61], v[130:133], v[192:195], v[58:61]
	v_mfma_f32_16x16x32_bf16 v[54:57], v[138:141], v[192:195], v[54:57]
	v_mfma_f32_16x16x32_bf16 v[126:129], v[130:133], v[200:203], v[126:129]
	v_mfma_f32_16x16x32_bf16 v[114:117], v[138:141], v[200:203], v[114:117]
	v_mfma_f32_16x16x32_bf16 v[118:121], v[134:137], v[180:183], v[118:121]
	v_mfma_f32_16x16x32_bf16 v[122:125], v[142:145], v[180:183], v[122:125]
	v_mfma_f32_16x16x32_bf16 v[78:81], v[134:137], v[188:191], v[78:81]
	v_mfma_f32_16x16x32_bf16 v[74:77], v[142:145], v[188:191], v[74:77]
	v_mfma_f32_16x16x32_bf16 v[58:61], v[134:137], v[196:199], v[58:61]
	v_mfma_f32_16x16x32_bf16 v[54:57], v[142:145], v[196:199], v[54:57]
	v_mfma_f32_16x16x32_bf16 v[126:129], v[134:137], v[204:207], v[126:129]
	v_mfma_f32_16x16x32_bf16 v[114:117], v[142:145], v[204:207], v[114:117]
	v_mfma_f32_16x16x32_bf16 v[110:113], v[146:149], v[176:179], v[110:113]
	v_mfma_f32_16x16x32_bf16 v[98:101], v[168:171], v[176:179], v[98:101]
	v_mfma_f32_16x16x32_bf16 v[70:73], v[146:149], v[184:187], v[70:73]
	v_mfma_f32_16x16x32_bf16 v[66:69], v[168:171], v[184:187], v[66:69]
	v_mfma_f32_16x16x32_bf16 v[42:45], v[146:149], v[192:195], v[42:45]
	v_mfma_f32_16x16x32_bf16 v[34:37], v[168:171], v[192:195], v[34:37]
	v_mfma_f32_16x16x32_bf16 v[102:105], v[146:149], v[200:203], v[102:105]
	v_mfma_f32_16x16x32_bf16 v[90:93], v[168:171], v[200:203], v[90:93]
	v_mfma_f32_16x16x32_bf16 v[110:113], v[150:153], v[180:183], v[110:113]
	v_mfma_f32_16x16x32_bf16 v[98:101], v[172:175], v[180:183], v[98:101]
	v_mfma_f32_16x16x32_bf16 v[70:73], v[150:153], v[188:191], v[70:73]
	v_mfma_f32_16x16x32_bf16 v[66:69], v[172:175], v[188:191], v[66:69]
	v_mfma_f32_16x16x32_bf16 v[42:45], v[150:153], v[196:199], v[42:45]
	v_mfma_f32_16x16x32_bf16 v[34:37], v[172:175], v[196:199], v[34:37]
	v_mfma_f32_16x16x32_bf16 v[102:105], v[150:153], v[204:207], v[102:105]
	v_mfma_f32_16x16x32_bf16 v[90:93], v[172:175], v[204:207], v[90:93]
	s_barrier
; #define PG8_STAGE(bufoff, gbase, voff) do { _Pragma("unroll") for (int _i = 0; _i < 2; ++_i) \
;         __builtin_amdgcn_global_load_lds((const unsigned*)((const char*)(gbase) + (voff)[_i]), (PG8_LAS unsigned*)(lds + (bufoff) + ldsw + _i * 8192), 16, 0, 0); } while (0)
; #define PG8_LDA(dst, b, h) do { _Pragma("unroll") for (int m = 0; m < 4; ++m) _Pragma("unroll") for (int k = 0; k < 2; ++k) dst[m][k] = *(const PG8_LAS bf16x8*)(lds + PG8_SA(b, h) + aoff + m * 2048 + k * 1024); } while (0)
; #define PG8_MMA(ai, bj, At, Bt) do { __builtin_amdgcn_s_setprio(1); _Pragma("unroll") for (int m = 0; m < 4; ++m) _Pragma("unroll") for (int n = 0; n < 2; ++n) _Pragma("unroll") for (int k = 0; k < 2; ++k) \
;         acc[ai][bj][m][n] = __builtin_amdgcn_mfma_f32_16x16x32_bf16(Bt[n][k], At[m][k], acc[ai][bj][m][n], 0, 0, 0); __builtin_amdgcn_s_setprio(0); } while (0)
; #define PG8_WAIT_V(n) asm volatile("s_waitcnt vmcnt(" #n ")" ::: "memory")
; #define PG8_WAIT_L(n) asm volatile("s_waitcnt lgkmcnt(" #n ")" ::: "memory")
; #define PG8_BAR __builtin_amdgcn_s_barrier()
; #define PG8_SCHED __builtin_amdgcn_sched_barrier(0)
; template <class Epi, class Sched, bool ALIGN_EPI = false, bool SP2 = false>
; __device__ __forceinline__ void gemm_phase(PG8_LAS unsigned char* lds, const Gemm g, const Sched& S, const Epi& E, volatile PG8_LAS unsigned* sw = nullptr) {
;     ...
;             PG8_LDA(At, 1, 1); PG8_STAGE(PG8_SB(1, 0), b3, voffB); PG8_STAGE(PG8_SB(1, 1), b3 + hstep, voffB); PG8_STAGE(PG8_SA(1, 0), a3, voffA);
;             PG8_WAIT_V(8); PG8_WAIT_L(0); PG8_BAR; PG8_MMA(1, 0, At, B0); PG8_MMA(1, 1, At, B1); PG8_BAR; PG8_SCHED;
;     ...
;         if constexpr (ALIGN_EPI) { if (wr == 0) PG8_BAR; }
	s_add_u32 s0, s6, 0x8000
	s_addc_u32 s1, s7, 0
	s_add_i32 s8, s86, s13
	v_lshl_add_u64 v[208:209], s[0:1], 0, v[156:157]
	s_mov_b32 m0, s8
	ds_read_b128 v[176:179], v232 offset:49152
	ds_read_b128 v[180:183], v232 offset:50176
	ds_read_b128 v[184:187], v232 offset:51200
	ds_read_b128 v[188:191], v232 offset:52224
	ds_read_b128 v[192:195], v232 offset:53248
	ds_read_b128 v[196:199], v232 offset:54272
	ds_read_b128 v[200:203], v232 offset:55296
	ds_read_b128 v[204:207], v232 offset:56320
	global_load_lds_dwordx4 v[208:209], off
	s_add_i32 m0, s8, 0x2000
	v_lshl_add_u64 v[208:209], s[0:1], 0, v[160:161]
	s_add_u32 s0, s6, 0xc000
	s_addc_u32 s1, s7, 0
	s_add_i32 s6, s87, s13
	global_load_lds_dwordx4 v[208:209], off
	v_lshl_add_u64 v[208:209], s[0:1], 0, v[156:157]
	s_mov_b32 m0, s6
	s_nop 0
	global_load_lds_dwordx4 v[208:209], off
	v_lshl_add_u64 v[208:209], s[0:1], 0, v[160:161]
	s_add_i32 m0, s6, 0x2000
	s_nop 0
	global_load_lds_dwordx4 v[208:209], off
	v_lshl_add_u64 v[208:209], s[4:5], 0, v[154:155]
	s_mov_b32 m0, s53
	s_nop 0
	global_load_lds_dwordx4 v[208:209], off
	v_lshl_add_u64 v[208:209], s[4:5], 0, v[158:159]
	s_mov_b32 m0, s55
	s_nop 0
	global_load_lds_dwordx4 v[208:209], off
	s_waitcnt vmcnt(8)
	s_waitcnt lgkmcnt(0)
	s_barrier
	s_waitcnt lgkmcnt(0)
	v_mfma_f32_16x16x32_bf16 v[94:97], v[130:133], v[176:179], v[94:97]
	v_mfma_f32_16x16x32_bf16 v[106:109], v[138:141], v[176:179], v[106:109]
	v_mfma_f32_16x16x32_bf16 v[38:41], v[130:133], v[184:187], v[38:41]
	v_mfma_f32_16x16x32_bf16 v[26:29], v[138:141], v[184:187], v[26:29]
	v_mfma_f32_16x16x32_bf16 v[46:49], v[130:133], v[192:195], v[46:49]
	v_mfma_f32_16x16x32_bf16 v[62:65], v[138:141], v[192:195], v[62:65]
	v_mfma_f32_16x16x32_bf16 v[2:5], v[130:133], v[200:203], v[2:5]
	v_mfma_f32_16x16x32_bf16 v[18:21], v[138:141], v[200:203], v[18:21]
	v_mfma_f32_16x16x32_bf16 v[94:97], v[134:137], v[180:183], v[94:97]
	v_mfma_f32_16x16x32_bf16 v[106:109], v[142:145], v[180:183], v[106:109]
	v_mfma_f32_16x16x32_bf16 v[38:41], v[134:137], v[188:191], v[38:41]
	v_mfma_f32_16x16x32_bf16 v[26:29], v[142:145], v[188:191], v[26:29]
	v_mfma_f32_16x16x32_bf16 v[46:49], v[134:137], v[196:199], v[46:49]
	v_mfma_f32_16x16x32_bf16 v[62:65], v[142:145], v[196:199], v[62:65]
	v_mfma_f32_16x16x32_bf16 v[2:5], v[134:137], v[204:207], v[2:5]
	v_mfma_f32_16x16x32_bf16 v[18:21], v[142:145], v[204:207], v[18:21]
	v_mfma_f32_16x16x32_bf16 v[86:89], v[146:149], v[176:179], v[86:89]
	v_mfma_f32_16x16x32_bf16 v[82:85], v[168:171], v[176:179], v[82:85]
	v_mfma_f32_16x16x32_bf16 v[14:17], v[146:149], v[184:187], v[14:17]
	v_mfma_f32_16x16x32_bf16 v[10:13], v[168:171], v[184:187], v[10:13]
	v_mfma_f32_16x16x32_bf16 v[30:33], v[146:149], v[192:195], v[30:33]
	v_mfma_f32_16x16x32_bf16 v[50:53], v[168:171], v[192:195], v[50:53]
	v_mfma_f32_16x16x32_bf16 v[6:9], v[146:149], v[200:203], v[6:9]
	v_mfma_f32_16x16x32_bf16 v[22:25], v[168:171], v[200:203], v[22:25]
	v_mfma_f32_16x16x32_bf16 v[86:89], v[150:153], v[180:183], v[86:89]
	v_mfma_f32_16x16x32_bf16 v[82:85], v[172:175], v[180:183], v[82:85]
	v_mfma_f32_16x16x32_bf16 v[14:17], v[150:153], v[188:191], v[14:17]
	v_mfma_f32_16x16x32_bf16 v[10:13], v[172:175], v[188:191], v[10:13]
	v_mfma_f32_16x16x32_bf16 v[30:33], v[150:153], v[196:199], v[30:33]
	v_mfma_f32_16x16x32_bf16 v[50:53], v[172:175], v[196:199], v[50:53]
	v_mfma_f32_16x16x32_bf16 v[6:9], v[150:153], v[204:207], v[6:9]
	v_mfma_f32_16x16x32_bf16 v[22:25], v[172:175], v[204:207], v[22:25]
	s_barrier
	s_add_i32 s85, s85, 2
	s_add_u32 s67, s67, 0x10000
	s_addc_u32 s84, s84, 0
	s_cmp_gt_u32 s85, 13
	s_mov_b64 s[0:1], s[2:3]
	s_cbranch_scc0 .LBB0_532
	s_and_b64 vcc, exec, s[28:29]
	s_cbranch_vccz .LBB0_535
	s_barrier
